# strategy 7.4 mirrored: waves 0-3 run the raised-priority copy of both GEMM K-loops
# speedup vs baseline: 1.0050x; 1.0032x over previous
; template <class Epi, class Sched, bool ALIGN_EPI = false, bool SP2 = false>
; __device__ __forceinline__ void gemm_phase(PG8_LAS unsigned char* lds, const Gemm g, const Sched& S, const Epi& E, int tid_in) {
;     ...
; #pragma unroll
;         for (int a = 0; a < 2; ++a)
; #pragma unroll
;             for (int b = 0; b < 2; ++b)
; #pragma unroll
;                 for (int m = 0; m < 4; ++m)
; #pragma unroll
;                     for (int n = 0; n < 2; ++n) acc[a][b][m][n] = (f32x4){0.f, 0.f, 0.f, 0.f};
;         cur = nxt; cA = nA; cB = nB; ++ui; ntc = PG8_KNT(cur.pn);
.LBB0_605:
	s_add_u32 s18, s40, 0x80
	s_addc_u32 s19, s41, 0
	s_add_u32 s20, s10, 0x100
	s_addc_u32 s21, s11, 0
	s_add_u32 s0, s2, 0x80
	s_addc_u32 s1, s3, 0
	s_waitcnt lgkmcnt(0)
	v_lshl_add_u64 v[130:131], s[0:1], 0, v[206:207]
	v_lshl_add_u64 v[132:133], s[0:1], 0, v[208:209]
	s_lshl_b64 s[0:1], s[94:95], 7
	v_mov_b32_e32 v2, 0
	s_add_u32 s22, s0, 0xffffff00
	s_mov_b32 s10, 0
	s_mov_b64 s[0:1], 0
	v_mov_b32_e32 v3, v2
	v_mov_b32_e32 v4, v2
	v_mov_b32_e32 v5, v2
	v_mov_b32_e32 v14, v2
	v_mov_b32_e32 v15, v2
	v_mov_b32_e32 v16, v2
	v_mov_b32_e32 v17, v2
	s_waitcnt vmcnt(0)
	v_mov_b32_e32 v22, v2
	v_mov_b32_e32 v23, v2
	v_mov_b32_e32 v24, v2
	v_mov_b32_e32 v25, v2
	v_mov_b32_e32 v30, v2
	v_mov_b32_e32 v31, v2
	v_mov_b32_e32 v32, v2
	v_mov_b32_e32 v33, v2
	v_mov_b32_e32 v38, v2
	v_mov_b32_e32 v39, v2
	v_mov_b32_e32 v40, v2
	v_mov_b32_e32 v41, v2
	v_mov_b32_e32 v46, v2
	v_mov_b32_e32 v47, v2
	v_mov_b32_e32 v48, v2
	v_mov_b32_e32 v49, v2
	v_mov_b32_e32 v54, v2
	v_mov_b32_e32 v55, v2
	v_mov_b32_e32 v56, v2
	v_mov_b32_e32 v57, v2
	v_mov_b32_e32 v62, v2
	v_mov_b32_e32 v63, v2
	v_mov_b32_e32 v64, v2
	v_mov_b32_e32 v65, v2
	v_mov_b32_e32 v6, v2
	v_mov_b32_e32 v7, v2
	v_mov_b32_e32 v8, v2
	v_mov_b32_e32 v9, v2
	v_mov_b32_e32 v10, v2
	v_mov_b32_e32 v11, v2
	v_mov_b32_e32 v12, v2
	v_mov_b32_e32 v13, v2
	v_mov_b32_e32 v18, v2
	v_mov_b32_e32 v19, v2
	v_mov_b32_e32 v20, v2
	v_mov_b32_e32 v21, v2
	v_mov_b32_e32 v26, v2
	v_mov_b32_e32 v27, v2
	v_mov_b32_e32 v28, v2
	v_mov_b32_e32 v29, v2
	v_mov_b32_e32 v34, v2
	v_mov_b32_e32 v35, v2
	v_mov_b32_e32 v36, v2
	v_mov_b32_e32 v37, v2
	v_mov_b32_e32 v42, v2
	v_mov_b32_e32 v43, v2
	v_mov_b32_e32 v44, v2
	v_mov_b32_e32 v45, v2
	v_mov_b32_e32 v50, v2
	v_mov_b32_e32 v51, v2
	v_mov_b32_e32 v52, v2
	v_mov_b32_e32 v53, v2
	v_mov_b32_e32 v58, v2
	v_mov_b32_e32 v59, v2
	v_mov_b32_e32 v60, v2
	v_mov_b32_e32 v61, v2
	v_mov_b32_e32 v70, v2
	v_mov_b32_e32 v71, v2
	v_mov_b32_e32 v72, v2
	v_mov_b32_e32 v73, v2
	v_mov_b32_e32 v78, v2
	v_mov_b32_e32 v79, v2
	v_mov_b32_e32 v80, v2
	v_mov_b32_e32 v81, v2
	v_mov_b32_e32 v86, v2
	v_mov_b32_e32 v87, v2
	v_mov_b32_e32 v88, v2
	v_mov_b32_e32 v89, v2
	v_mov_b32_e32 v94, v2
	v_mov_b32_e32 v95, v2
	v_mov_b32_e32 v96, v2
	v_mov_b32_e32 v97, v2
	v_mov_b32_e32 v102, v2
	v_mov_b32_e32 v103, v2
	v_mov_b32_e32 v104, v2
	v_mov_b32_e32 v105, v2
	v_mov_b32_e32 v110, v2
	v_mov_b32_e32 v111, v2
	v_mov_b32_e32 v112, v2
	v_mov_b32_e32 v113, v2
	v_mov_b32_e32 v118, v2
	v_mov_b32_e32 v119, v2
	v_mov_b32_e32 v120, v2
	v_mov_b32_e32 v121, v2
	v_mov_b32_e32 v126, v2
	v_mov_b32_e32 v127, v2
	v_mov_b32_e32 v128, v2
	v_mov_b32_e32 v129, v2
	v_mov_b32_e32 v66, v2
	v_mov_b32_e32 v67, v2
	v_mov_b32_e32 v68, v2
	v_mov_b32_e32 v69, v2
	v_mov_b32_e32 v74, v2
	v_mov_b32_e32 v75, v2
	v_mov_b32_e32 v76, v2
	v_mov_b32_e32 v77, v2
	v_mov_b32_e32 v82, v2
	v_mov_b32_e32 v83, v2
	v_mov_b32_e32 v84, v2
	v_mov_b32_e32 v85, v2
	v_mov_b32_e32 v90, v2
	v_mov_b32_e32 v91, v2
	v_mov_b32_e32 v92, v2
	v_mov_b32_e32 v93, v2
	v_mov_b32_e32 v98, v2
	v_mov_b32_e32 v99, v2
	v_mov_b32_e32 v100, v2
	v_mov_b32_e32 v101, v2
	v_mov_b32_e32 v106, v2
	v_mov_b32_e32 v107, v2
	v_mov_b32_e32 v108, v2
	v_mov_b32_e32 v109, v2
	v_mov_b32_e32 v114, v2
	v_mov_b32_e32 v115, v2
	v_mov_b32_e32 v116, v2
	v_mov_b32_e32 v117, v2
	v_mov_b32_e32 v122, v2
	v_mov_b32_e32 v123, v2
	v_mov_b32_e32 v124, v2
	v_mov_b32_e32 v125, v2
	v_readlane_b32 s101, v255, 15
	s_cmp_ge_u32 s101, 4
	s_cbranch_scc0 .Lyk0_loop

; template <class Epi, class Sched, bool ALIGN_EPI = false, bool SP2 = false>
; __device__ __forceinline__ void gemm_phase(PG8_LAS unsigned char* lds, const Gemm g, const Sched& S, const Epi& E, int tid_in) {
;     ...
; #pragma unroll
;         for (int a = 0; a < 2; ++a)
; #pragma unroll
;             for (int b = 0; b < 2; ++b)
; #pragma unroll
;                 for (int m = 0; m < 4; ++m)
; #pragma unroll
;                     for (int n = 0; n < 2; ++n) acc[a][b][m][n] = (f32x4){0.f, 0.f, 0.f, 0.f};
;         cur = nxt; cA = nA; cB = nB; ++ui; ntc = PG8_KNT(cur.pn);
.LBB0_1179:
	s_add_u32 s21, s48, 0x80
	s_addc_u32 s53, s49, 0
	s_add_u32 s54, s8, 0x100
	v_mov_b32_e32 v8, 0
	s_addc_u32 s55, s9, 0
	s_mov_b32 s0, 0
	s_mov_b32 s56, s79
	v_mov_b32_e32 v9, v8
	v_mov_b32_e32 v10, v8
	v_mov_b32_e32 v11, v8
	v_mov_b32_e32 v16, v8
	v_mov_b32_e32 v17, v8
	v_mov_b32_e32 v18, v8
	v_mov_b32_e32 v19, v8
	v_mov_b32_e32 v24, v8
	v_mov_b32_e32 v25, v8
	v_mov_b32_e32 v26, v8
	v_mov_b32_e32 v27, v8
	v_mov_b32_e32 v32, v8
	v_mov_b32_e32 v33, v8
	v_mov_b32_e32 v34, v8
	v_mov_b32_e32 v35, v8
	v_mov_b32_e32 v40, v8
	v_mov_b32_e32 v41, v8
	v_mov_b32_e32 v42, v8
	v_mov_b32_e32 v43, v8
	v_mov_b32_e32 v48, v8
	v_mov_b32_e32 v49, v8
	v_mov_b32_e32 v50, v8
	v_mov_b32_e32 v51, v8
	v_mov_b32_e32 v56, v8
	v_mov_b32_e32 v57, v8
	v_mov_b32_e32 v58, v8
	v_mov_b32_e32 v59, v8
	v_mov_b32_e32 v64, v8
	v_mov_b32_e32 v65, v8
	v_mov_b32_e32 v66, v8
	v_mov_b32_e32 v67, v8
	v_mov_b32_e32 v4, v8
	v_mov_b32_e32 v5, v8
	v_mov_b32_e32 v6, v8
	v_mov_b32_e32 v7, v8
	v_mov_b32_e32 v12, v8
	v_mov_b32_e32 v13, v8
	v_mov_b32_e32 v14, v8
	v_mov_b32_e32 v15, v8
	v_mov_b32_e32 v20, v8
	v_mov_b32_e32 v21, v8
	v_mov_b32_e32 v22, v8
	v_mov_b32_e32 v23, v8
	v_mov_b32_e32 v28, v8
	v_mov_b32_e32 v29, v8
	v_mov_b32_e32 v30, v8
	v_mov_b32_e32 v31, v8
	v_mov_b32_e32 v36, v8
	v_mov_b32_e32 v37, v8
	v_mov_b32_e32 v38, v8
	v_mov_b32_e32 v39, v8
	v_mov_b32_e32 v44, v8
	v_mov_b32_e32 v45, v8
	v_mov_b32_e32 v46, v8
	v_mov_b32_e32 v47, v8
	v_mov_b32_e32 v52, v8
	v_mov_b32_e32 v53, v8
	v_mov_b32_e32 v54, v8
	v_mov_b32_e32 v55, v8
	v_mov_b32_e32 v60, v8
	v_mov_b32_e32 v61, v8
	v_mov_b32_e32 v62, v8
	v_mov_b32_e32 v63, v8
	v_mov_b32_e32 v72, v8
	v_mov_b32_e32 v73, v8
	v_mov_b32_e32 v74, v8
	v_mov_b32_e32 v75, v8
	v_mov_b32_e32 v80, v8
	v_mov_b32_e32 v81, v8
	v_mov_b32_e32 v82, v8
	v_mov_b32_e32 v83, v8
	v_mov_b32_e32 v88, v8
	v_mov_b32_e32 v89, v8
	v_mov_b32_e32 v90, v8
	v_mov_b32_e32 v91, v8
	v_mov_b32_e32 v96, v8
	v_mov_b32_e32 v97, v8
	v_mov_b32_e32 v98, v8
	v_mov_b32_e32 v99, v8
	v_mov_b32_e32 v104, v8
	v_mov_b32_e32 v105, v8
	v_mov_b32_e32 v106, v8
	v_mov_b32_e32 v107, v8
	v_mov_b32_e32 v112, v8
	v_mov_b32_e32 v113, v8
	v_mov_b32_e32 v114, v8
	v_mov_b32_e32 v115, v8
	v_mov_b32_e32 v120, v8
	v_mov_b32_e32 v121, v8
	v_mov_b32_e32 v122, v8
	v_mov_b32_e32 v123, v8
	v_mov_b32_e32 v128, v8
	v_mov_b32_e32 v129, v8
	v_mov_b32_e32 v130, v8
	v_mov_b32_e32 v131, v8
	v_mov_b32_e32 v68, v8
	v_mov_b32_e32 v69, v8
	v_mov_b32_e32 v70, v8
	v_mov_b32_e32 v71, v8
	v_mov_b32_e32 v76, v8
	v_mov_b32_e32 v77, v8
	v_mov_b32_e32 v78, v8
	v_mov_b32_e32 v79, v8
	v_mov_b32_e32 v84, v8
	v_mov_b32_e32 v85, v8
	v_mov_b32_e32 v86, v8
	v_mov_b32_e32 v87, v8
	v_mov_b32_e32 v92, v8
	v_mov_b32_e32 v93, v8
	v_mov_b32_e32 v94, v8
	v_mov_b32_e32 v95, v8
	v_mov_b32_e32 v100, v8
	v_mov_b32_e32 v101, v8
	v_mov_b32_e32 v102, v8
	v_mov_b32_e32 v103, v8
	v_mov_b32_e32 v108, v8
	v_mov_b32_e32 v109, v8
	v_mov_b32_e32 v110, v8
	v_mov_b32_e32 v111, v8
	v_mov_b32_e32 v116, v8
	v_mov_b32_e32 v117, v8
	v_mov_b32_e32 v118, v8
	v_mov_b32_e32 v119, v8
	v_mov_b32_e32 v124, v8
	v_mov_b32_e32 v125, v8
	v_mov_b32_e32 v126, v8
	v_mov_b32_e32 v127, v8
	s_waitcnt vmcnt(0)
	v_readlane_b32 s101, v255, 15
	s_cmp_ge_u32 s101, 4
	s_cbranch_scc0 .Lyk1_loop
